# GEMM steady K-loops: loop-exit test moved before MFMA group 5, next-tile header/address code interleaved between group-5 MFMAs (off the path to the tile-end barrier), flag code after the barrier
# baseline (speedup 1.0000x reference)
; DEVI f32x4 mfma16(bf16x8 a, bf16x8 b, f32x4 c) { return __builtin_amdgcn_mfma_f32_16x16x32_bf16(a, b, c, 0, 0, 0); }
; template <int MODE, class Epi>
; DEVI void gemm256_phase(int sw, const bf16_t* __restrict__ W, int ldw, const bf16_t* __restrict__ X, int ldx, int K, int nN, char* shm, const Epi& epi) {
;     ...
; #pragma unroll
;       for (int ks = 0; ks < 2; ++ks) {
;         const int kx = (wid >> 2) ? (1 - 2 * ks) * 1024 : 0;
;         bf16x8 At[8], Bf[4];
; #pragma unroll
;         for (int m = 0; m < 8; ++m) At[m] = *(const bf16x8*)(SAp + (2 * m + ks) * 1024 + kx);
; #pragma unroll
;         for (int n = 0; n < 4; ++n) Bf[n] = *(const bf16x8*)(SBp + (2 * n + ks) * 1024 + kx);
; #pragma unroll
;         for (int m = 0; m < 8; ++m)
; #pragma unroll
;           for (int n = 0; n < 4; ++n) acc[m][n] = mfma16(At[m], Bf[n], acc[m][n]);
;         __builtin_amdgcn_sched_barrier(0);
;         if (ks == 0 && wid >= 4) {
;           if (st_own) stage(cur ^ 1, n0, m0, kt0 + t + 1);
;           else if (st_next) stage(cur ^ 1, n1, m1, kt1);
;         }
;       }
;       asm volatile("s_waitcnt vmcnt(0)" ::: "memory");
;       __syncthreads();
.LBB0_167:
.Lmy_xs_168:
	s_waitcnt lgkmcnt(3)
	v_mfma_f32_16x16x32_bf16 v[124:127], v[220:223], v[134:137], v[124:127]
	v_mfma_f32_16x16x32_bf16 v[120:123], v[220:223], v[138:141], v[120:123]
	v_mfma_f32_16x16x32_bf16 v[116:119], v[220:223], v[142:145], v[116:119]
	v_mfma_f32_16x16x32_bf16 v[112:115], v[220:223], v[146:149], v[112:115]
	ds_read_b128 v[236:239], v150 offset:9216
	s_waitcnt lgkmcnt(3)
	v_mfma_f32_16x16x32_bf16 v[108:111], v[224:227], v[134:137], v[108:111]
	v_mfma_f32_16x16x32_bf16 v[104:107], v[224:227], v[138:141], v[104:107]
	v_mfma_f32_16x16x32_bf16 v[100:103], v[224:227], v[142:145], v[100:103]
	v_mfma_f32_16x16x32_bf16 v[96:99], v[224:227], v[146:149], v[96:99]
	ds_read_b128 v[240:243], v150 offset:11264
	s_waitcnt lgkmcnt(3)
	v_mfma_f32_16x16x32_bf16 v[92:95], v[228:231], v[134:137], v[92:95]
	v_mfma_f32_16x16x32_bf16 v[88:91], v[228:231], v[138:141], v[88:91]
	v_mfma_f32_16x16x32_bf16 v[84:87], v[228:231], v[142:145], v[84:87]
	v_mfma_f32_16x16x32_bf16 v[80:83], v[228:231], v[146:149], v[80:83]
	ds_read_b128 v[244:247], v150 offset:13312
	s_waitcnt lgkmcnt(3)
	v_mfma_f32_16x16x32_bf16 v[76:79], v[232:235], v[134:137], v[76:79]
	v_mfma_f32_16x16x32_bf16 v[72:75], v[232:235], v[138:141], v[72:75]
	v_mfma_f32_16x16x32_bf16 v[68:71], v[232:235], v[142:145], v[68:71]
	v_mfma_f32_16x16x32_bf16 v[64:67], v[232:235], v[146:149], v[64:67]
	ds_read_b128 v[248:251], v150 offset:15360
	s_waitcnt lgkmcnt(3)
	v_mfma_f32_16x16x32_bf16 v[60:63], v[236:239], v[134:137], v[60:63]
	v_mfma_f32_16x16x32_bf16 v[56:59], v[236:239], v[138:141], v[56:59]
	v_mfma_f32_16x16x32_bf16 v[52:55], v[236:239], v[142:145], v[52:55]
	v_mfma_f32_16x16x32_bf16 v[48:51], v[236:239], v[146:149], v[48:51]
	s_addk_i32 s67, 0x80
	s_cmp_eq_u32 s66, s68
	s_cbranch_scc1 .Lmy_xexit_168
	s_waitcnt lgkmcnt(2)
	v_mfma_f32_16x16x32_bf16 v[44:47], v[240:243], v[134:137], v[44:47]
	s_add_i32 s0, s45, s68
	s_and_b32 s69, s0, 1
	s_add_i32 s68, s68, 1
	v_mfma_f32_16x16x32_bf16 v[40:43], v[240:243], v[138:141], v[40:43]
	s_lshl_b32 s10, s69, 16
	s_add_i32 s11, s10, s47
	v_add_u32_e32 v129, s11, v194
	v_add_u32_e32 v253, s53, v129
	v_mfma_f32_16x16x32_bf16 v[36:39], v[240:243], v[142:145], v[36:39]
	s_or_b32 s11, s10, s52
	v_add_u32_e32 v128, s11, v194
	v_add_u32_e32 v252, s53, v128
	v_mfma_f32_16x16x32_bf16 v[32:35], v[240:243], v[146:149], v[32:35]
	s_waitcnt lgkmcnt(0)
	s_waitcnt vmcnt(0)
	s_barrier
	ds_read_b128 v[220:223], v253
	v_mfma_f32_16x16x32_bf16 v[28:31], v[244:247], v[134:137], v[28:31]
	v_mfma_f32_16x16x32_bf16 v[12:15], v[248:251], v[134:137], v[12:15]
	ds_read_b128 v[134:137], v252 offset:32768
	v_mfma_f32_16x16x32_bf16 v[24:27], v[244:247], v[138:141], v[24:27]
	v_mfma_f32_16x16x32_bf16 v[8:11], v[248:251], v[138:141], v[8:11]
	ds_read_b128 v[138:141], v252 offset:34816
	s_cmp_lt_i32 s68, s46
	s_cselect_b64 s[0:1], -1, 0
	s_cmp_ge_i32 s68, s46
	s_cselect_b64 s[8:9], -1, 0
	v_cndmask_b32_e64 v254, 0, 1, s[0:1]
	s_and_b64 s[8:9], s[2:3], s[8:9]
	s_andn2_b64 vcc, exec, s[36:37]
	v_cmp_ne_u32_e64 s[0:1], 1, v254
	v_mfma_f32_16x16x32_bf16 v[20:23], v[244:247], v[142:145], v[20:23]
	v_mfma_f32_16x16x32_bf16 v[4:7], v[248:251], v[142:145], v[4:7]
	ds_read_b128 v[142:145], v252 offset:36864
	v_mfma_f32_16x16x32_bf16 v[16:19], v[244:247], v[146:149], v[16:19]
	v_mfma_f32_16x16x32_bf16 v[0:3], v[248:251], v[146:149], v[0:3]
	ds_read_b128 v[146:149], v252 offset:38912
	ds_read_b128 v[224:227], v253 offset:2048
	ds_read_b128 v[228:231], v253 offset:4096
	ds_read_b128 v[232:235], v253 offset:6144
	v_mov_b32_e32 v150, v253
	s_branch .Lmy_xf_168
.Lmy_xexit_168:
	s_waitcnt lgkmcnt(2)
	v_mfma_f32_16x16x32_bf16 v[44:47], v[240:243], v[134:137], v[44:47]
	v_mfma_f32_16x16x32_bf16 v[40:43], v[240:243], v[138:141], v[40:43]
	v_mfma_f32_16x16x32_bf16 v[36:39], v[240:243], v[142:145], v[36:39]
	v_mfma_f32_16x16x32_bf16 v[32:35], v[240:243], v[146:149], v[32:35]
	s_waitcnt lgkmcnt(1)
	v_mfma_f32_16x16x32_bf16 v[28:31], v[244:247], v[134:137], v[28:31]
	v_mfma_f32_16x16x32_bf16 v[24:27], v[244:247], v[138:141], v[24:27]
	v_mfma_f32_16x16x32_bf16 v[20:23], v[244:247], v[142:145], v[20:23]
	v_mfma_f32_16x16x32_bf16 v[16:19], v[244:247], v[146:149], v[16:19]
	s_waitcnt lgkmcnt(0)
	v_mfma_f32_16x16x32_bf16 v[12:15], v[248:251], v[134:137], v[12:15]
	v_mfma_f32_16x16x32_bf16 v[8:11], v[248:251], v[138:141], v[8:11]
	v_mfma_f32_16x16x32_bf16 v[4:7], v[248:251], v[142:145], v[4:7]
	v_mfma_f32_16x16x32_bf16 v[0:3], v[248:251], v[146:149], v[0:3]
	s_waitcnt vmcnt(0)
	s_barrier
	s_branch .LBB0_186

; DEVI f32x4 mfma16(bf16x8 a, bf16x8 b, f32x4 c) { return __builtin_amdgcn_mfma_f32_16x16x32_bf16(a, b, c, 0, 0, 0); }
; template <int MODE, class Epi>
; DEVI void gemm256_phase(int sw, const bf16_t* __restrict__ W, int ldw, const bf16_t* __restrict__ X, int ldx, int K, int nN, char* shm, const Epi& epi) {
;     ...
; #pragma unroll
;       for (int ks = 0; ks < 2; ++ks) {
;         const int kx = (wid >> 2) ? (1 - 2 * ks) * 1024 : 0;
;         bf16x8 At[8], Bf[4];
; #pragma unroll
;         for (int m = 0; m < 8; ++m) At[m] = *(const bf16x8*)(SAp + (2 * m + ks) * 1024 + kx);
; #pragma unroll
;         for (int n = 0; n < 4; ++n) Bf[n] = *(const bf16x8*)(SBp + (2 * n + ks) * 1024 + kx);
; #pragma unroll
;         for (int m = 0; m < 8; ++m)
; #pragma unroll
;           for (int n = 0; n < 4; ++n) acc[m][n] = mfma16(At[m], Bf[n], acc[m][n]);
;         __builtin_amdgcn_sched_barrier(0);
;         if (ks == 0 && wid >= 4) {
;           if (st_own) stage(cur ^ 1, n0, m0, kt0 + t + 1);
;           else if (st_next) stage(cur ^ 1, n1, m1, kt1);
;         }
;       }
;       asm volatile("s_waitcnt vmcnt(0)" ::: "memory");
;       __syncthreads();
.LBB0_703:
.Lmy_xs_704:
	s_waitcnt lgkmcnt(2)
	v_mfma_f32_16x16x32_bf16 v[124:127], v[220:223], v[134:137], v[124:127]
	v_mfma_f32_16x16x32_bf16 v[120:123], v[220:223], v[142:145], v[120:123]
	v_mfma_f32_16x16x32_bf16 v[116:119], v[220:223], v[146:149], v[116:119]
	v_mfma_f32_16x16x32_bf16 v[112:115], v[220:223], v[150:153], v[112:115]
	ds_read_b128 v[236:239], v154 offset:9216
	s_waitcnt lgkmcnt(3)
	v_mfma_f32_16x16x32_bf16 v[108:111], v[224:227], v[134:137], v[108:111]
	v_mfma_f32_16x16x32_bf16 v[104:107], v[224:227], v[142:145], v[104:107]
	v_mfma_f32_16x16x32_bf16 v[100:103], v[224:227], v[146:149], v[100:103]
	v_mfma_f32_16x16x32_bf16 v[96:99], v[224:227], v[150:153], v[96:99]
	ds_read_b128 v[240:243], v154 offset:11264
	s_waitcnt lgkmcnt(3)
	v_mfma_f32_16x16x32_bf16 v[92:95], v[228:231], v[134:137], v[92:95]
	v_mfma_f32_16x16x32_bf16 v[88:91], v[228:231], v[142:145], v[88:91]
	v_mfma_f32_16x16x32_bf16 v[84:87], v[228:231], v[146:149], v[84:87]
	v_mfma_f32_16x16x32_bf16 v[80:83], v[228:231], v[150:153], v[80:83]
	ds_read_b128 v[244:247], v154 offset:13312
	s_waitcnt lgkmcnt(3)
	v_mfma_f32_16x16x32_bf16 v[76:79], v[232:235], v[134:137], v[76:79]
	v_mfma_f32_16x16x32_bf16 v[72:75], v[232:235], v[142:145], v[72:75]
	v_mfma_f32_16x16x32_bf16 v[68:71], v[232:235], v[146:149], v[68:71]
	v_mfma_f32_16x16x32_bf16 v[64:67], v[232:235], v[150:153], v[64:67]
	ds_read_b128 v[248:251], v154 offset:15360
	s_waitcnt lgkmcnt(3)
	v_mfma_f32_16x16x32_bf16 v[60:63], v[236:239], v[134:137], v[60:63]
	v_mfma_f32_16x16x32_bf16 v[56:59], v[236:239], v[142:145], v[56:59]
	v_mfma_f32_16x16x32_bf16 v[52:55], v[236:239], v[146:149], v[52:55]
	v_mfma_f32_16x16x32_bf16 v[48:51], v[236:239], v[150:153], v[48:51]
	s_addk_i32 s81, 0x80
	s_cmp_eq_u32 s80, s82
	s_cbranch_scc1 .Lmy_xexit_704
	s_waitcnt lgkmcnt(2)
	v_mfma_f32_16x16x32_bf16 v[44:47], v[240:243], v[134:137], v[44:47]
	s_add_i32 s0, s61, s82
	s_and_b32 s83, s0, 1
	s_add_i32 s82, s82, 1
	v_mfma_f32_16x16x32_bf16 v[40:43], v[240:243], v[142:145], v[40:43]
	s_lshl_b32 s42, s83, 16
	s_add_i32 s43, s42, s58
	v_add_u32_e32 v129, s43, v194
	v_add_u32_e32 v253, s62, v129
	v_mfma_f32_16x16x32_bf16 v[36:39], v[240:243], v[146:149], v[36:39]
	s_or_b32 s43, s42, s59
	v_add_u32_e32 v128, s43, v194
	v_add_u32_e32 v252, s62, v128
	v_mfma_f32_16x16x32_bf16 v[32:35], v[240:243], v[150:153], v[32:35]
	s_waitcnt lgkmcnt(0)
	s_waitcnt vmcnt(0)
	s_barrier
	ds_read_b128 v[220:223], v253
	ds_read_b128 v[138:141], v252 offset:34816
	v_mfma_f32_16x16x32_bf16 v[28:31], v[244:247], v[134:137], v[28:31]
	v_mfma_f32_16x16x32_bf16 v[12:15], v[248:251], v[134:137], v[12:15]
	ds_read_b128 v[134:137], v252 offset:32768
	v_mfma_f32_16x16x32_bf16 v[24:27], v[244:247], v[142:145], v[24:27]
	v_mfma_f32_16x16x32_bf16 v[8:11], v[248:251], v[142:145], v[8:11]
	ds_read_b128 v[142:145], v252 offset:36864
	s_cmp_lt_i32 s82, s54
	s_cselect_b64 s[0:1], -1, 0
	s_cmp_ge_i32 s82, s54
	s_cselect_b64 s[40:41], -1, 0
	v_cmp_ne_u32_e32 vcc, 1, v197
	v_cndmask_b32_e64 v254, 0, 1, s[0:1]
	s_and_b64 s[40:41], s[38:39], s[40:41]
	v_cmp_ne_u32_e64 s[0:1], 1, v254
	v_mfma_f32_16x16x32_bf16 v[20:23], v[244:247], v[146:149], v[20:23]
	v_mfma_f32_16x16x32_bf16 v[4:7], v[248:251], v[146:149], v[4:7]
	ds_read_b128 v[146:149], v252 offset:38912
	v_mfma_f32_16x16x32_bf16 v[16:19], v[244:247], v[150:153], v[16:19]
	v_mfma_f32_16x16x32_bf16 v[0:3], v[248:251], v[150:153], v[0:3]
	ds_read_b128 v[224:227], v253 offset:2048
	ds_read_b128 v[228:231], v253 offset:4096
	ds_read_b128 v[232:235], v253 offset:6144
	v_mov_b32_e32 v150, v253
	s_branch .Lmy_xf_704
.Lmy_xexit_704:
	s_waitcnt lgkmcnt(2)
	v_mfma_f32_16x16x32_bf16 v[44:47], v[240:243], v[134:137], v[44:47]
	v_mfma_f32_16x16x32_bf16 v[40:43], v[240:243], v[142:145], v[40:43]
	v_mfma_f32_16x16x32_bf16 v[36:39], v[240:243], v[146:149], v[36:39]
	v_mfma_f32_16x16x32_bf16 v[32:35], v[240:243], v[150:153], v[32:35]
	s_waitcnt lgkmcnt(1)
	v_mfma_f32_16x16x32_bf16 v[28:31], v[244:247], v[134:137], v[28:31]
	v_mfma_f32_16x16x32_bf16 v[24:27], v[244:247], v[142:145], v[24:27]
	v_mfma_f32_16x16x32_bf16 v[20:23], v[244:247], v[146:149], v[20:23]
	v_mfma_f32_16x16x32_bf16 v[16:19], v[244:247], v[150:153], v[16:19]
	s_waitcnt lgkmcnt(0)
	v_mfma_f32_16x16x32_bf16 v[12:15], v[248:251], v[134:137], v[12:15]
	v_mfma_f32_16x16x32_bf16 v[8:11], v[248:251], v[142:145], v[8:11]
	v_mfma_f32_16x16x32_bf16 v[4:7], v[248:251], v[146:149], v[4:7]
	v_mfma_f32_16x16x32_bf16 v[0:3], v[248:251], v[150:153], v[0:3]
	s_waitcnt vmcnt(0)
	s_barrier
	s_branch .LBB0_724

; DEVI f32x4 mfma16(bf16x8 a, bf16x8 b, f32x4 c) { return __builtin_amdgcn_mfma_f32_16x16x32_bf16(a, b, c, 0, 0, 0); }
; template <int MODE, class Epi>
; DEVI void gemm256_phase(int sw, const bf16_t* __restrict__ W, int ldw, const bf16_t* __restrict__ X, int ldx, int K, int nN, char* shm, const Epi& epi) {
;     ...
; #pragma unroll
;       for (int ks = 0; ks < 2; ++ks) {
;         const int kx = (wid >> 2) ? (1 - 2 * ks) * 1024 : 0;
;         bf16x8 At[8], Bf[4];
; #pragma unroll
;         for (int m = 0; m < 8; ++m) At[m] = *(const bf16x8*)(SAp + (2 * m + ks) * 1024 + kx);
; #pragma unroll
;         for (int n = 0; n < 4; ++n) Bf[n] = *(const bf16x8*)(SBp + (2 * n + ks) * 1024 + kx);
; #pragma unroll
;         for (int m = 0; m < 8; ++m)
; #pragma unroll
;           for (int n = 0; n < 4; ++n) acc[m][n] = mfma16(At[m], Bf[n], acc[m][n]);
;         __builtin_amdgcn_sched_barrier(0);
;         if (ks == 0 && wid >= 4) {
;           if (st_own) stage(cur ^ 1, n0, m0, kt0 + t + 1);
;           else if (st_next) stage(cur ^ 1, n1, m1, kt1);
;         }
;       }
;       asm volatile("s_waitcnt vmcnt(0)" ::: "memory");
;       __syncthreads();
.LBB0_984:
.Lmy_xs_985:
	s_waitcnt lgkmcnt(2)
	v_mfma_f32_16x16x32_bf16 v[124:127], v[220:223], v[134:137], v[124:127]
	v_mfma_f32_16x16x32_bf16 v[120:123], v[220:223], v[142:145], v[120:123]
	v_mfma_f32_16x16x32_bf16 v[116:119], v[220:223], v[146:149], v[116:119]
	v_mfma_f32_16x16x32_bf16 v[112:115], v[220:223], v[150:153], v[112:115]
	ds_read_b128 v[236:239], v154 offset:9216
	s_waitcnt lgkmcnt(3)
	v_mfma_f32_16x16x32_bf16 v[108:111], v[224:227], v[134:137], v[108:111]
	v_mfma_f32_16x16x32_bf16 v[104:107], v[224:227], v[142:145], v[104:107]
	v_mfma_f32_16x16x32_bf16 v[100:103], v[224:227], v[146:149], v[100:103]
	v_mfma_f32_16x16x32_bf16 v[96:99], v[224:227], v[150:153], v[96:99]
	ds_read_b128 v[240:243], v154 offset:11264
	s_waitcnt lgkmcnt(3)
	v_mfma_f32_16x16x32_bf16 v[92:95], v[228:231], v[134:137], v[92:95]
	v_mfma_f32_16x16x32_bf16 v[88:91], v[228:231], v[142:145], v[88:91]
	v_mfma_f32_16x16x32_bf16 v[84:87], v[228:231], v[146:149], v[84:87]
	v_mfma_f32_16x16x32_bf16 v[80:83], v[228:231], v[150:153], v[80:83]
	ds_read_b128 v[244:247], v154 offset:13312
	s_waitcnt lgkmcnt(3)
	v_mfma_f32_16x16x32_bf16 v[76:79], v[232:235], v[134:137], v[76:79]
	v_mfma_f32_16x16x32_bf16 v[72:75], v[232:235], v[142:145], v[72:75]
	v_mfma_f32_16x16x32_bf16 v[68:71], v[232:235], v[146:149], v[68:71]
	v_mfma_f32_16x16x32_bf16 v[64:67], v[232:235], v[150:153], v[64:67]
	ds_read_b128 v[248:251], v154 offset:15360
	s_waitcnt lgkmcnt(3)
	v_mfma_f32_16x16x32_bf16 v[60:63], v[236:239], v[134:137], v[60:63]
	v_mfma_f32_16x16x32_bf16 v[56:59], v[236:239], v[142:145], v[56:59]
	v_mfma_f32_16x16x32_bf16 v[52:55], v[236:239], v[146:149], v[52:55]
	v_mfma_f32_16x16x32_bf16 v[48:51], v[236:239], v[150:153], v[48:51]
	s_addk_i32 s57, 0x80
	s_cmp_eq_u32 s54, s58
	s_cbranch_scc1 .Lmy_xexit_985
	s_waitcnt lgkmcnt(2)
	v_mfma_f32_16x16x32_bf16 v[44:47], v[240:243], v[134:137], v[44:47]
	s_add_i32 s10, s37, s58
	s_and_b32 s60, s10, 1
	s_mov_b64 s[10:11], -1
	s_and_b64 vcc, exec, s[4:5]
	v_mfma_f32_16x16x32_bf16 v[40:43], v[240:243], v[142:145], v[40:43]
	s_lshl_b32 s59, s60, 16
	s_add_i32 s10, s59, s38
	v_add_u32_e32 v129, s10, v198
	v_add_u32_e32 v253, s41, v129
	v_mfma_f32_16x16x32_bf16 v[36:39], v[240:243], v[146:149], v[36:39]
	s_add_i32 s10, s59, s39
	v_add_u32_e32 v128, s10, v198
	v_add_u32_e32 v252, s41, v128
	v_mfma_f32_16x16x32_bf16 v[32:35], v[240:243], v[150:153], v[32:35]
	s_waitcnt lgkmcnt(0)
	s_waitcnt vmcnt(0)
	s_barrier
	ds_read_b128 v[220:223], v253
	ds_read_b128 v[224:227], v253 offset:2048
	v_mfma_f32_16x16x32_bf16 v[28:31], v[244:247], v[134:137], v[28:31]
	v_mfma_f32_16x16x32_bf16 v[12:15], v[248:251], v[134:137], v[12:15]
	ds_read_b128 v[134:137], v252 offset:32768
	v_mfma_f32_16x16x32_bf16 v[24:27], v[244:247], v[142:145], v[24:27]
	v_mfma_f32_16x16x32_bf16 v[8:11], v[248:251], v[142:145], v[8:11]
	ds_read_b128 v[142:145], v252 offset:34816
	v_mfma_f32_16x16x32_bf16 v[20:23], v[244:247], v[146:149], v[20:23]
	v_mfma_f32_16x16x32_bf16 v[4:7], v[248:251], v[146:149], v[4:7]
	ds_read_b128 v[146:149], v252 offset:36864
	v_mfma_f32_16x16x32_bf16 v[16:19], v[244:247], v[150:153], v[16:19]
	v_mfma_f32_16x16x32_bf16 v[0:3], v[248:251], v[150:153], v[0:3]
	ds_read_b128 v[150:153], v252 offset:38912
	ds_read_b128 v[228:231], v253 offset:4096
	ds_read_b128 v[232:235], v253 offset:6144
	v_mov_b32_e32 v154, v253
	s_branch .Lmy_xf_985

; DEVI f32x4 mfma16(bf16x8 a, bf16x8 b, f32x4 c) { return __builtin_amdgcn_mfma_f32_16x16x32_bf16(a, b, c, 0, 0, 0); }
; template <int MODE, class Epi>
; DEVI void gemm256_phase(int sw, const bf16_t* __restrict__ W, int ldw, const bf16_t* __restrict__ X, int ldx, int K, int nN, char* shm, const Epi& epi) {
;     ...
; #pragma unroll
;       for (int ks = 0; ks < 2; ++ks) {
;         const int kx = (wid >> 2) ? (1 - 2 * ks) * 1024 : 0;
;         bf16x8 At[8], Bf[4];
; #pragma unroll
;         for (int m = 0; m < 8; ++m) At[m] = *(const bf16x8*)(SAp + (2 * m + ks) * 1024 + kx);
; #pragma unroll
;         for (int n = 0; n < 4; ++n) Bf[n] = *(const bf16x8*)(SBp + (2 * n + ks) * 1024 + kx);
; #pragma unroll
;         for (int m = 0; m < 8; ++m)
; #pragma unroll
;           for (int n = 0; n < 4; ++n) acc[m][n] = mfma16(At[m], Bf[n], acc[m][n]);
;         __builtin_amdgcn_sched_barrier(0);
;         if (ks == 0 && wid >= 4) {
;           if (st_own) stage(cur ^ 1, n0, m0, kt0 + t + 1);
;           else if (st_next) stage(cur ^ 1, n1, m1, kt1);
;         }
;       }
;       asm volatile("s_waitcnt vmcnt(0)" ::: "memory");
;       __syncthreads();
.LBB0_1033:
.Lmy_xs_1034:
	s_waitcnt lgkmcnt(2)
	v_mfma_f32_16x16x32_bf16 v[124:127], v[220:223], v[134:137], v[124:127]
	v_mfma_f32_16x16x32_bf16 v[120:123], v[220:223], v[142:145], v[120:123]
	v_mfma_f32_16x16x32_bf16 v[116:119], v[220:223], v[146:149], v[116:119]
	v_mfma_f32_16x16x32_bf16 v[112:115], v[220:223], v[150:153], v[112:115]
	ds_read_b128 v[236:239], v154 offset:9216
	s_waitcnt lgkmcnt(3)
	v_mfma_f32_16x16x32_bf16 v[108:111], v[224:227], v[134:137], v[108:111]
	v_mfma_f32_16x16x32_bf16 v[104:107], v[224:227], v[142:145], v[104:107]
	v_mfma_f32_16x16x32_bf16 v[100:103], v[224:227], v[146:149], v[100:103]
	v_mfma_f32_16x16x32_bf16 v[96:99], v[224:227], v[150:153], v[96:99]
	ds_read_b128 v[240:243], v154 offset:11264
	s_waitcnt lgkmcnt(3)
	v_mfma_f32_16x16x32_bf16 v[92:95], v[228:231], v[134:137], v[92:95]
	v_mfma_f32_16x16x32_bf16 v[88:91], v[228:231], v[142:145], v[88:91]
	v_mfma_f32_16x16x32_bf16 v[84:87], v[228:231], v[146:149], v[84:87]
	v_mfma_f32_16x16x32_bf16 v[80:83], v[228:231], v[150:153], v[80:83]
	ds_read_b128 v[244:247], v154 offset:13312
	s_waitcnt lgkmcnt(3)
	v_mfma_f32_16x16x32_bf16 v[76:79], v[232:235], v[134:137], v[76:79]
	v_mfma_f32_16x16x32_bf16 v[72:75], v[232:235], v[142:145], v[72:75]
	v_mfma_f32_16x16x32_bf16 v[68:71], v[232:235], v[146:149], v[68:71]
	v_mfma_f32_16x16x32_bf16 v[64:67], v[232:235], v[150:153], v[64:67]
	ds_read_b128 v[248:251], v154 offset:15360
	s_waitcnt lgkmcnt(3)
	v_mfma_f32_16x16x32_bf16 v[60:63], v[236:239], v[134:137], v[60:63]
	v_mfma_f32_16x16x32_bf16 v[56:59], v[236:239], v[142:145], v[56:59]
	v_mfma_f32_16x16x32_bf16 v[52:55], v[236:239], v[146:149], v[52:55]
	v_mfma_f32_16x16x32_bf16 v[48:51], v[236:239], v[150:153], v[48:51]
	s_addk_i32 s81, 0x80
	s_cmp_eq_u32 s80, s82
	s_cbranch_scc1 .Lmy_xexit_1034
	s_waitcnt lgkmcnt(2)
	v_mfma_f32_16x16x32_bf16 v[44:47], v[240:243], v[134:137], v[44:47]
	s_add_i32 s0, s61, s82
	s_and_b32 s83, s0, 1
	s_add_i32 s82, s82, 1
	v_mfma_f32_16x16x32_bf16 v[40:43], v[240:243], v[142:145], v[40:43]
	s_lshl_b32 s42, s83, 16
	s_add_i32 s43, s42, s58
	v_add_u32_e32 v129, s43, v194
	v_add_u32_e32 v253, s62, v129
	v_mfma_f32_16x16x32_bf16 v[36:39], v[240:243], v[146:149], v[36:39]
	s_or_b32 s43, s42, s59
	v_add_u32_e32 v128, s43, v194
	v_add_u32_e32 v252, s62, v128
	v_mfma_f32_16x16x32_bf16 v[32:35], v[240:243], v[150:153], v[32:35]
	s_waitcnt lgkmcnt(0)
	s_waitcnt vmcnt(0)
	s_barrier
	ds_read_b128 v[220:223], v253
	ds_read_b128 v[224:227], v253 offset:2048
	v_mfma_f32_16x16x32_bf16 v[28:31], v[244:247], v[134:137], v[28:31]
	v_mfma_f32_16x16x32_bf16 v[12:15], v[248:251], v[134:137], v[12:15]
	ds_read_b128 v[134:137], v252 offset:32768
	v_mfma_f32_16x16x32_bf16 v[24:27], v[244:247], v[142:145], v[24:27]
	v_mfma_f32_16x16x32_bf16 v[8:11], v[248:251], v[142:145], v[8:11]
	ds_read_b128 v[142:145], v252 offset:34816
	s_cmp_lt_i32 s82, s54
	s_cselect_b64 s[0:1], -1, 0
	s_cmp_ge_i32 s82, s54
	s_cselect_b64 s[40:41], -1, 0
	v_cmp_ne_u32_e32 vcc, 1, v197
	v_cndmask_b32_e64 v254, 0, 1, s[0:1]
	s_and_b64 s[40:41], s[38:39], s[40:41]
	v_cmp_ne_u32_e64 s[0:1], 1, v254
	v_mfma_f32_16x16x32_bf16 v[20:23], v[244:247], v[146:149], v[20:23]
	v_mfma_f32_16x16x32_bf16 v[4:7], v[248:251], v[146:149], v[4:7]
	ds_read_b128 v[146:149], v252 offset:36864
	v_mfma_f32_16x16x32_bf16 v[16:19], v[244:247], v[150:153], v[16:19]
	v_mfma_f32_16x16x32_bf16 v[0:3], v[248:251], v[150:153], v[0:3]
	ds_read_b128 v[150:153], v252 offset:38912
	ds_read_b128 v[228:231], v253 offset:4096
	ds_read_b128 v[232:235], v253 offset:6144
	v_mov_b32_e32 v154, v253
	s_branch .Lmy_xf_1034

; DEVI f32x4 mfma16(bf16x8 a, bf16x8 b, f32x4 c) { return __builtin_amdgcn_mfma_f32_16x16x32_bf16(a, b, c, 0, 0, 0); }
; template <int MODE, class Epi>
; DEVI void gemm256_phase(int sw, const bf16_t* __restrict__ W, int ldw, const bf16_t* __restrict__ X, int ldx, int K, int nN, char* shm, const Epi& epi) {
;     ...
; #pragma unroll
;       for (int ks = 0; ks < 2; ++ks) {
;         const int kx = (wid >> 2) ? (1 - 2 * ks) * 1024 : 0;
;         bf16x8 At[8], Bf[4];
; #pragma unroll
;         for (int m = 0; m < 8; ++m) At[m] = *(const bf16x8*)(SAp + (2 * m + ks) * 1024 + kx);
; #pragma unroll
;         for (int n = 0; n < 4; ++n) Bf[n] = *(const bf16x8*)(SBp + (2 * n + ks) * 1024 + kx);
; #pragma unroll
;         for (int m = 0; m < 8; ++m)
; #pragma unroll
;           for (int n = 0; n < 4; ++n) acc[m][n] = mfma16(At[m], Bf[n], acc[m][n]);
;         __builtin_amdgcn_sched_barrier(0);
;         if (ks == 0 && wid >= 4) {
;           if (st_own) stage(cur ^ 1, n0, m0, kt0 + t + 1);
;           else if (st_next) stage(cur ^ 1, n1, m1, kt1);
;         }
;       }
;       asm volatile("s_waitcnt vmcnt(0)" ::: "memory");
;       __syncthreads();
.LBB0_1269:
.Lmy_xs_1270:
	s_waitcnt lgkmcnt(2)
	v_mfma_f32_16x16x32_bf16 v[124:127], v[220:223], v[134:137], v[124:127]
	v_mfma_f32_16x16x32_bf16 v[120:123], v[220:223], v[142:145], v[120:123]
	v_mfma_f32_16x16x32_bf16 v[116:119], v[220:223], v[146:149], v[116:119]
	v_mfma_f32_16x16x32_bf16 v[112:115], v[220:223], v[150:153], v[112:115]
	ds_read_b128 v[236:239], v154 offset:9216
	s_waitcnt lgkmcnt(3)
	v_mfma_f32_16x16x32_bf16 v[108:111], v[224:227], v[134:137], v[108:111]
	v_mfma_f32_16x16x32_bf16 v[104:107], v[224:227], v[142:145], v[104:107]
	v_mfma_f32_16x16x32_bf16 v[100:103], v[224:227], v[146:149], v[100:103]
	v_mfma_f32_16x16x32_bf16 v[96:99], v[224:227], v[150:153], v[96:99]
	ds_read_b128 v[240:243], v154 offset:11264
	s_waitcnt lgkmcnt(3)
	v_mfma_f32_16x16x32_bf16 v[92:95], v[228:231], v[134:137], v[92:95]
	v_mfma_f32_16x16x32_bf16 v[88:91], v[228:231], v[142:145], v[88:91]
	v_mfma_f32_16x16x32_bf16 v[84:87], v[228:231], v[146:149], v[84:87]
	v_mfma_f32_16x16x32_bf16 v[80:83], v[228:231], v[150:153], v[80:83]
	ds_read_b128 v[244:247], v154 offset:13312
	s_waitcnt lgkmcnt(3)
	v_mfma_f32_16x16x32_bf16 v[76:79], v[232:235], v[134:137], v[76:79]
	v_mfma_f32_16x16x32_bf16 v[72:75], v[232:235], v[142:145], v[72:75]
	v_mfma_f32_16x16x32_bf16 v[68:71], v[232:235], v[146:149], v[68:71]
	v_mfma_f32_16x16x32_bf16 v[64:67], v[232:235], v[150:153], v[64:67]
	ds_read_b128 v[248:251], v154 offset:15360
	s_waitcnt lgkmcnt(3)
	v_mfma_f32_16x16x32_bf16 v[60:63], v[236:239], v[134:137], v[60:63]
	v_mfma_f32_16x16x32_bf16 v[56:59], v[236:239], v[142:145], v[56:59]
	v_mfma_f32_16x16x32_bf16 v[52:55], v[236:239], v[146:149], v[52:55]
	v_mfma_f32_16x16x32_bf16 v[48:51], v[236:239], v[150:153], v[48:51]
	s_addk_i32 s72, 0x80
	s_cmp_eq_u32 s71, s73
	s_cbranch_scc1 .Lmy_xexit_1270
	s_waitcnt lgkmcnt(2)
	v_mfma_f32_16x16x32_bf16 v[44:47], v[240:243], v[134:137], v[44:47]
	s_add_i32 s0, s49, s73
	s_and_b32 s74, s0, 1
	s_add_i32 s73, s73, 1
	v_mfma_f32_16x16x32_bf16 v[40:43], v[240:243], v[142:145], v[40:43]
	s_lshl_b32 s10, s74, 16
	s_add_i32 s11, s10, s55
	v_add_u32_e32 v129, s11, v194
	v_add_u32_e32 v253, s57, v129
	v_mfma_f32_16x16x32_bf16 v[36:39], v[240:243], v[146:149], v[36:39]
	s_or_b32 s11, s10, s56
	v_add_u32_e32 v128, s11, v194
	v_add_u32_e32 v252, s57, v128
	v_mfma_f32_16x16x32_bf16 v[32:35], v[240:243], v[150:153], v[32:35]
	s_waitcnt lgkmcnt(0)
	s_waitcnt vmcnt(0)
	s_barrier
	ds_read_b128 v[220:223], v253
	ds_read_b128 v[224:227], v253 offset:2048
	v_mfma_f32_16x16x32_bf16 v[28:31], v[244:247], v[134:137], v[28:31]
	v_mfma_f32_16x16x32_bf16 v[12:15], v[248:251], v[134:137], v[12:15]
	ds_read_b128 v[134:137], v252 offset:32768
	v_mfma_f32_16x16x32_bf16 v[24:27], v[244:247], v[142:145], v[24:27]
	v_mfma_f32_16x16x32_bf16 v[8:11], v[248:251], v[142:145], v[8:11]
	ds_read_b128 v[142:145], v252 offset:34816
	s_cmp_lt_i32 s73, s54
	s_cselect_b64 s[0:1], -1, 0
	s_cmp_ge_i32 s73, s54
	s_cselect_b64 s[8:9], -1, 0
	v_cndmask_b32_e64 v254, 0, 1, s[0:1]
	s_and_b64 s[8:9], s[2:3], s[8:9]
	s_andn2_b64 vcc, exec, s[40:41]
	v_cmp_ne_u32_e64 s[0:1], 1, v254
	v_mfma_f32_16x16x32_bf16 v[20:23], v[244:247], v[146:149], v[20:23]
	v_mfma_f32_16x16x32_bf16 v[4:7], v[248:251], v[146:149], v[4:7]
	ds_read_b128 v[146:149], v252 offset:36864
	v_mfma_f32_16x16x32_bf16 v[16:19], v[244:247], v[150:153], v[16:19]
	v_mfma_f32_16x16x32_bf16 v[0:3], v[248:251], v[150:153], v[0:3]
	ds_read_b128 v[150:153], v252 offset:38912
	ds_read_b128 v[228:231], v253 offset:4096
	ds_read_b128 v[232:235], v253 offset:6144
	v_mov_b32_e32 v154, v253
	s_branch .Lmy_xf_1270

; DEVI f32x4 mfma16(bf16x8 a, bf16x8 b, f32x4 c) { return __builtin_amdgcn_mfma_f32_16x16x32_bf16(a, b, c, 0, 0, 0); }
; template <int MODE, class Epi>
; DEVI void gemm256_phase(int sw, const bf16_t* __restrict__ W, int ldw, const bf16_t* __restrict__ X, int ldx, int K, int nN, char* shm, const Epi& epi) {
;     ...
; #pragma unroll
;       for (int ks = 0; ks < 2; ++ks) {
;         const int kx = (wid >> 2) ? (1 - 2 * ks) * 1024 : 0;
;         bf16x8 At[8], Bf[4];
; #pragma unroll
;         for (int m = 0; m < 8; ++m) At[m] = *(const bf16x8*)(SAp + (2 * m + ks) * 1024 + kx);
; #pragma unroll
;         for (int n = 0; n < 4; ++n) Bf[n] = *(const bf16x8*)(SBp + (2 * n + ks) * 1024 + kx);
; #pragma unroll
;         for (int m = 0; m < 8; ++m)
; #pragma unroll
;           for (int n = 0; n < 4; ++n) acc[m][n] = mfma16(At[m], Bf[n], acc[m][n]);
;         __builtin_amdgcn_sched_barrier(0);
;         if (ks == 0 && wid >= 4) {
;           if (st_own) stage(cur ^ 1, n0, m0, kt0 + t + 1);
;           else if (st_next) stage(cur ^ 1, n1, m1, kt1);
;         }
;       }
;       asm volatile("s_waitcnt vmcnt(0)" ::: "memory");
;       __syncthreads();
.LBB0_1677:
.Lmy_xs_1678:
	s_waitcnt lgkmcnt(2)
	v_mfma_f32_16x16x32_bf16 v[124:127], v[220:223], v[134:137], v[124:127]
	v_mfma_f32_16x16x32_bf16 v[120:123], v[220:223], v[142:145], v[120:123]
	v_mfma_f32_16x16x32_bf16 v[116:119], v[220:223], v[146:149], v[116:119]
	v_mfma_f32_16x16x32_bf16 v[112:115], v[220:223], v[150:153], v[112:115]
	ds_read_b128 v[236:239], v154 offset:9216
	s_waitcnt lgkmcnt(3)
	v_mfma_f32_16x16x32_bf16 v[108:111], v[224:227], v[134:137], v[108:111]
	v_mfma_f32_16x16x32_bf16 v[104:107], v[224:227], v[142:145], v[104:107]
	v_mfma_f32_16x16x32_bf16 v[100:103], v[224:227], v[146:149], v[100:103]
	v_mfma_f32_16x16x32_bf16 v[96:99], v[224:227], v[150:153], v[96:99]
	ds_read_b128 v[240:243], v154 offset:11264
	s_waitcnt lgkmcnt(3)
	v_mfma_f32_16x16x32_bf16 v[92:95], v[228:231], v[134:137], v[92:95]
	v_mfma_f32_16x16x32_bf16 v[88:91], v[228:231], v[142:145], v[88:91]
	v_mfma_f32_16x16x32_bf16 v[84:87], v[228:231], v[146:149], v[84:87]
	v_mfma_f32_16x16x32_bf16 v[80:83], v[228:231], v[150:153], v[80:83]
	ds_read_b128 v[244:247], v154 offset:13312
	s_waitcnt lgkmcnt(3)
	v_mfma_f32_16x16x32_bf16 v[76:79], v[232:235], v[134:137], v[76:79]
	v_mfma_f32_16x16x32_bf16 v[72:75], v[232:235], v[142:145], v[72:75]
	v_mfma_f32_16x16x32_bf16 v[68:71], v[232:235], v[146:149], v[68:71]
	v_mfma_f32_16x16x32_bf16 v[64:67], v[232:235], v[150:153], v[64:67]
	ds_read_b128 v[248:251], v154 offset:15360
	s_waitcnt lgkmcnt(3)
	v_mfma_f32_16x16x32_bf16 v[60:63], v[236:239], v[134:137], v[60:63]
	v_mfma_f32_16x16x32_bf16 v[56:59], v[236:239], v[142:145], v[56:59]
	v_mfma_f32_16x16x32_bf16 v[52:55], v[236:239], v[146:149], v[52:55]
	v_mfma_f32_16x16x32_bf16 v[48:51], v[236:239], v[150:153], v[48:51]
	s_addk_i32 s78, 0x80
	s_cmp_eq_u32 s77, s79
	s_cbranch_scc1 .Lmy_xexit_1678
	s_waitcnt lgkmcnt(2)
	v_mfma_f32_16x16x32_bf16 v[44:47], v[240:243], v[134:137], v[44:47]
	s_add_i32 s2, s61, s79
	s_and_b32 s80, s2, 1
	s_add_i32 s79, s79, 1
	v_mfma_f32_16x16x32_bf16 v[40:43], v[240:243], v[142:145], v[40:43]
	s_lshl_b32 s42, s80, 16
	s_add_i32 s16, s42, s57
	v_add_u32_e32 v129, s16, v194
	v_add_u32_e32 v253, s62, v129
	v_mfma_f32_16x16x32_bf16 v[36:39], v[240:243], v[146:149], v[36:39]
	s_or_b32 s16, s42, s58
	v_add_u32_e32 v128, s16, v194
	v_add_u32_e32 v252, s62, v128
	v_mfma_f32_16x16x32_bf16 v[32:35], v[240:243], v[150:153], v[32:35]
	s_waitcnt lgkmcnt(0)
	s_waitcnt vmcnt(0)
	s_barrier
	ds_read_b128 v[220:223], v253
	ds_read_b128 v[224:227], v253 offset:2048
	v_mfma_f32_16x16x32_bf16 v[28:31], v[244:247], v[134:137], v[28:31]
	v_mfma_f32_16x16x32_bf16 v[12:15], v[248:251], v[134:137], v[12:15]
	ds_read_b128 v[134:137], v252 offset:32768
	v_mfma_f32_16x16x32_bf16 v[24:27], v[244:247], v[142:145], v[24:27]
	v_mfma_f32_16x16x32_bf16 v[8:11], v[248:251], v[142:145], v[8:11]
	ds_read_b128 v[142:145], v252 offset:34816
	s_cmp_lt_i32 s79, s60
	s_cselect_b64 s[2:3], -1, 0
	s_cmp_ge_i32 s79, s60
	s_cselect_b64 s[40:41], -1, 0
	v_cndmask_b32_e64 v254, 0, 1, s[2:3]
	s_and_b64 s[40:41], s[34:35], s[40:41]
	s_and_b64 vcc, exec, s[0:1]
	v_cmp_ne_u32_e64 s[2:3], 1, v254
	v_mfma_f32_16x16x32_bf16 v[20:23], v[244:247], v[146:149], v[20:23]
	v_mfma_f32_16x16x32_bf16 v[4:7], v[248:251], v[146:149], v[4:7]
	ds_read_b128 v[146:149], v252 offset:36864
	v_mfma_f32_16x16x32_bf16 v[16:19], v[244:247], v[150:153], v[16:19]
	v_mfma_f32_16x16x32_bf16 v[0:3], v[248:251], v[150:153], v[0:3]
	ds_read_b128 v[150:153], v252 offset:38912
	ds_read_b128 v[228:231], v253 offset:4096
	ds_read_b128 v[232:235], v253 offset:6144
	v_mov_b32_e32 v154, v253
	s_branch .Lmy_xf_1678

; DEVI f32x4 mfma16(bf16x8 a, bf16x8 b, f32x4 c) { return __builtin_amdgcn_mfma_f32_16x16x32_bf16(a, b, c, 0, 0, 0); }
; template <int MODE, class Epi>
; DEVI void gemm256_phase(int sw, const bf16_t* __restrict__ W, int ldw, const bf16_t* __restrict__ X, int ldx, int K, int nN, char* shm, const Epi& epi) {
;     ...
; #pragma unroll
;       for (int ks = 0; ks < 2; ++ks) {
;         const int kx = (wid >> 2) ? (1 - 2 * ks) * 1024 : 0;
;         bf16x8 At[8], Bf[4];
; #pragma unroll
;         for (int m = 0; m < 8; ++m) At[m] = *(const bf16x8*)(SAp + (2 * m + ks) * 1024 + kx);
; #pragma unroll
;         for (int n = 0; n < 4; ++n) Bf[n] = *(const bf16x8*)(SBp + (2 * n + ks) * 1024 + kx);
; #pragma unroll
;         for (int m = 0; m < 8; ++m)
; #pragma unroll
;           for (int n = 0; n < 4; ++n) acc[m][n] = mfma16(At[m], Bf[n], acc[m][n]);
;         __builtin_amdgcn_sched_barrier(0);
;         if (ks == 0 && wid >= 4) {
;           if (st_own) stage(cur ^ 1, n0, m0, kt0 + t + 1);
;           else if (st_next) stage(cur ^ 1, n1, m1, kt1);
;         }
;       }
;       asm volatile("s_waitcnt vmcnt(0)" ::: "memory");
;       __syncthreads();
.LBB0_1759:
.Lmy_xs_1760:
	s_waitcnt lgkmcnt(2)
	v_mfma_f32_16x16x32_bf16 v[124:127], v[220:223], v[134:137], v[124:127]
	v_mfma_f32_16x16x32_bf16 v[120:123], v[220:223], v[142:145], v[120:123]
	v_mfma_f32_16x16x32_bf16 v[116:119], v[220:223], v[146:149], v[116:119]
	v_mfma_f32_16x16x32_bf16 v[112:115], v[220:223], v[150:153], v[112:115]
	ds_read_b128 v[236:239], v154 offset:9216
	s_waitcnt lgkmcnt(3)
	v_mfma_f32_16x16x32_bf16 v[108:111], v[224:227], v[134:137], v[108:111]
	v_mfma_f32_16x16x32_bf16 v[104:107], v[224:227], v[142:145], v[104:107]
	v_mfma_f32_16x16x32_bf16 v[100:103], v[224:227], v[146:149], v[100:103]
	v_mfma_f32_16x16x32_bf16 v[96:99], v[224:227], v[150:153], v[96:99]
	ds_read_b128 v[240:243], v154 offset:11264
	s_waitcnt lgkmcnt(3)
	v_mfma_f32_16x16x32_bf16 v[92:95], v[228:231], v[134:137], v[92:95]
	v_mfma_f32_16x16x32_bf16 v[88:91], v[228:231], v[142:145], v[88:91]
	v_mfma_f32_16x16x32_bf16 v[84:87], v[228:231], v[146:149], v[84:87]
	v_mfma_f32_16x16x32_bf16 v[80:83], v[228:231], v[150:153], v[80:83]
	ds_read_b128 v[244:247], v154 offset:13312
	s_waitcnt lgkmcnt(3)
	v_mfma_f32_16x16x32_bf16 v[76:79], v[232:235], v[134:137], v[76:79]
	v_mfma_f32_16x16x32_bf16 v[72:75], v[232:235], v[142:145], v[72:75]
	v_mfma_f32_16x16x32_bf16 v[68:71], v[232:235], v[146:149], v[68:71]
	v_mfma_f32_16x16x32_bf16 v[64:67], v[232:235], v[150:153], v[64:67]
	ds_read_b128 v[248:251], v154 offset:15360
	s_waitcnt lgkmcnt(3)
	v_mfma_f32_16x16x32_bf16 v[60:63], v[236:239], v[134:137], v[60:63]
	v_mfma_f32_16x16x32_bf16 v[56:59], v[236:239], v[142:145], v[56:59]
	v_mfma_f32_16x16x32_bf16 v[52:55], v[236:239], v[146:149], v[52:55]
	v_mfma_f32_16x16x32_bf16 v[48:51], v[236:239], v[150:153], v[48:51]
	s_addk_i32 s49, 0x80
	s_cmp_eq_u32 s46, s50
	s_cbranch_scc1 .Lmy_xexit_1760
	s_waitcnt lgkmcnt(2)
	v_mfma_f32_16x16x32_bf16 v[44:47], v[240:243], v[134:137], v[44:47]
	s_add_i32 s10, s31, s50
	s_and_b32 s52, s10, 1
	s_mov_b64 s[10:11], -1
	s_and_b64 vcc, exec, s[4:5]
	v_mfma_f32_16x16x32_bf16 v[40:43], v[240:243], v[142:145], v[40:43]
	s_lshl_b32 s51, s52, 16
	s_add_i32 s10, s51, s34
	v_add_u32_e32 v129, s10, v198
	v_add_u32_e32 v253, s37, v129
	v_mfma_f32_16x16x32_bf16 v[36:39], v[240:243], v[146:149], v[36:39]
	s_add_i32 s10, s51, s35
	v_add_u32_e32 v128, s10, v198
	v_add_u32_e32 v252, s37, v128
	v_mfma_f32_16x16x32_bf16 v[32:35], v[240:243], v[150:153], v[32:35]
	s_waitcnt lgkmcnt(0)
	s_waitcnt vmcnt(0)
	s_barrier
	ds_read_b128 v[220:223], v253
	ds_read_b128 v[224:227], v253 offset:2048
	v_mfma_f32_16x16x32_bf16 v[28:31], v[244:247], v[134:137], v[28:31]
	v_mfma_f32_16x16x32_bf16 v[12:15], v[248:251], v[134:137], v[12:15]
	ds_read_b128 v[134:137], v252 offset:32768
	v_mfma_f32_16x16x32_bf16 v[24:27], v[244:247], v[142:145], v[24:27]
	v_mfma_f32_16x16x32_bf16 v[8:11], v[248:251], v[142:145], v[8:11]
	ds_read_b128 v[142:145], v252 offset:34816
	v_mfma_f32_16x16x32_bf16 v[20:23], v[244:247], v[146:149], v[20:23]
	v_mfma_f32_16x16x32_bf16 v[4:7], v[248:251], v[146:149], v[4:7]
	ds_read_b128 v[146:149], v252 offset:36864
	v_mfma_f32_16x16x32_bf16 v[16:19], v[244:247], v[150:153], v[16:19]
	v_mfma_f32_16x16x32_bf16 v[0:3], v[248:251], v[150:153], v[0:3]
	ds_read_b128 v[150:153], v252 offset:38912
	ds_read_b128 v[228:231], v253 offset:4096
	ds_read_b128 v[232:235], v253 offset:6144
	v_mov_b32_e32 v154, v253
	s_branch .Lmy_xf_1760

; DEVI f32x4 mfma16(bf16x8 a, bf16x8 b, f32x4 c) { return __builtin_amdgcn_mfma_f32_16x16x32_bf16(a, b, c, 0, 0, 0); }
; template <int MODE, class Epi>
; DEVI void gemm256_phase(int sw, const bf16_t* __restrict__ W, int ldw, const bf16_t* __restrict__ X, int ldx, int K, int nN, char* shm, const Epi& epi) {
;     ...
; #pragma unroll
;       for (int ks = 0; ks < 2; ++ks) {
;         const int kx = (wid >> 2) ? (1 - 2 * ks) * 1024 : 0;
;         bf16x8 At[8], Bf[4];
; #pragma unroll
;         for (int m = 0; m < 8; ++m) At[m] = *(const bf16x8*)(SAp + (2 * m + ks) * 1024 + kx);
; #pragma unroll
;         for (int n = 0; n < 4; ++n) Bf[n] = *(const bf16x8*)(SBp + (2 * n + ks) * 1024 + kx);
; #pragma unroll
;         for (int m = 0; m < 8; ++m)
; #pragma unroll
;           for (int n = 0; n < 4; ++n) acc[m][n] = mfma16(At[m], Bf[n], acc[m][n]);
;         __builtin_amdgcn_sched_barrier(0);
;         if (ks == 0 && wid >= 4) {
;           if (st_own) stage(cur ^ 1, n0, m0, kt0 + t + 1);
;           else if (st_next) stage(cur ^ 1, n1, m1, kt1);
;         }
;       }
;       asm volatile("s_waitcnt vmcnt(0)" ::: "memory");
;       __syncthreads();
.LBB0_1800:
.Lmy_xs_1801:
	s_waitcnt lgkmcnt(2)
	v_mfma_f32_16x16x32_bf16 v[124:127], v[220:223], v[134:137], v[124:127]
	v_mfma_f32_16x16x32_bf16 v[120:123], v[220:223], v[142:145], v[120:123]
	v_mfma_f32_16x16x32_bf16 v[116:119], v[220:223], v[146:149], v[116:119]
	v_mfma_f32_16x16x32_bf16 v[112:115], v[220:223], v[150:153], v[112:115]
	ds_read_b128 v[236:239], v154 offset:9216
	s_waitcnt lgkmcnt(3)
	v_mfma_f32_16x16x32_bf16 v[108:111], v[224:227], v[134:137], v[108:111]
	v_mfma_f32_16x16x32_bf16 v[104:107], v[224:227], v[142:145], v[104:107]
	v_mfma_f32_16x16x32_bf16 v[100:103], v[224:227], v[146:149], v[100:103]
	v_mfma_f32_16x16x32_bf16 v[96:99], v[224:227], v[150:153], v[96:99]
	ds_read_b128 v[240:243], v154 offset:11264
	s_waitcnt lgkmcnt(3)
	v_mfma_f32_16x16x32_bf16 v[92:95], v[228:231], v[134:137], v[92:95]
	v_mfma_f32_16x16x32_bf16 v[88:91], v[228:231], v[142:145], v[88:91]
	v_mfma_f32_16x16x32_bf16 v[84:87], v[228:231], v[146:149], v[84:87]
	v_mfma_f32_16x16x32_bf16 v[80:83], v[228:231], v[150:153], v[80:83]
	ds_read_b128 v[244:247], v154 offset:13312
	s_waitcnt lgkmcnt(3)
	v_mfma_f32_16x16x32_bf16 v[76:79], v[232:235], v[134:137], v[76:79]
	v_mfma_f32_16x16x32_bf16 v[72:75], v[232:235], v[142:145], v[72:75]
	v_mfma_f32_16x16x32_bf16 v[68:71], v[232:235], v[146:149], v[68:71]
	v_mfma_f32_16x16x32_bf16 v[64:67], v[232:235], v[150:153], v[64:67]
	ds_read_b128 v[248:251], v154 offset:15360
	s_waitcnt lgkmcnt(3)
	v_mfma_f32_16x16x32_bf16 v[60:63], v[236:239], v[134:137], v[60:63]
	v_mfma_f32_16x16x32_bf16 v[56:59], v[236:239], v[142:145], v[56:59]
	v_mfma_f32_16x16x32_bf16 v[52:55], v[236:239], v[146:149], v[52:55]
	v_mfma_f32_16x16x32_bf16 v[48:51], v[236:239], v[150:153], v[48:51]
	s_addk_i32 s69, 0x80
	s_cmp_eq_u32 s68, s70
	s_cbranch_scc1 .Lmy_xexit_1801
	s_waitcnt lgkmcnt(2)
	v_mfma_f32_16x16x32_bf16 v[44:47], v[240:243], v[134:137], v[44:47]
	s_add_i32 s2, s52, s70
	s_and_b32 s71, s2, 1
	s_add_i32 s70, s70, 1
	v_mfma_f32_16x16x32_bf16 v[40:43], v[240:243], v[142:145], v[40:43]
	s_lshl_b32 s38, s71, 16
	s_add_i32 s16, s38, s49
	v_add_u32_e32 v129, s16, v194
	v_add_u32_e32 v253, s53, v129
	v_mfma_f32_16x16x32_bf16 v[36:39], v[240:243], v[146:149], v[36:39]
	s_or_b32 s16, s38, s50
	v_add_u32_e32 v128, s16, v194
	v_add_u32_e32 v252, s53, v128
	v_mfma_f32_16x16x32_bf16 v[32:35], v[240:243], v[150:153], v[32:35]
	s_waitcnt lgkmcnt(0)
	s_waitcnt vmcnt(0)
	s_barrier
	ds_read_b128 v[220:223], v253
	ds_read_b128 v[224:227], v253 offset:2048
	v_mfma_f32_16x16x32_bf16 v[28:31], v[244:247], v[134:137], v[28:31]
	v_mfma_f32_16x16x32_bf16 v[12:15], v[248:251], v[134:137], v[12:15]
	ds_read_b128 v[134:137], v252 offset:32768
	v_mfma_f32_16x16x32_bf16 v[24:27], v[244:247], v[142:145], v[24:27]
	v_mfma_f32_16x16x32_bf16 v[8:11], v[248:251], v[142:145], v[8:11]
	ds_read_b128 v[142:145], v252 offset:34816
	s_cmp_lt_i32 s70, s58
	s_cselect_b64 s[2:3], -1, 0
	s_cmp_ge_i32 s70, s58
	s_cselect_b64 s[36:37], -1, 0
	v_cndmask_b32_e64 v254, 0, 1, s[2:3]
	s_and_b64 s[36:37], s[28:29], s[36:37]
	s_and_b64 vcc, exec, s[0:1]
	v_cmp_ne_u32_e64 s[2:3], 1, v254
	v_mfma_f32_16x16x32_bf16 v[20:23], v[244:247], v[146:149], v[20:23]
	v_mfma_f32_16x16x32_bf16 v[4:7], v[248:251], v[146:149], v[4:7]
	ds_read_b128 v[146:149], v252 offset:36864
	v_mfma_f32_16x16x32_bf16 v[16:19], v[244:247], v[150:153], v[16:19]
	v_mfma_f32_16x16x32_bf16 v[0:3], v[248:251], v[150:153], v[0:3]
	ds_read_b128 v[150:153], v252 offset:38912
	ds_read_b128 v[228:231], v253 offset:4096
	ds_read_b128 v[232:235], v253 offset:6144
	v_mov_b32_e32 v154, v253
	s_branch .Lmy_xf_1801
